# in-proj GEMM runs 9 full rounds; its 64 left-over tiles (gate columns of rows 32..36, needed only by the projection phase) run at the start of the pooling/kv phase on workgroups 0..63, static item spl
# speedup vs baseline: 1.0038x; 1.0038x over previous
; __device__ __forceinline__ int launder(int v) { asm volatile("" : "+v"(v)); return v; }
; __device__ __forceinline__ void run_phase(const Params& p, int ph, LAS unsigned char* lds, const int tid, const int bid) {
;     ...
;         SchedPlain S; S.init(MPAD, NIN, G, bid); S.A = pws(p) + OFF_XB; S.Bt = pws(p) + OFF_WIN + l * SZ_WIN; S.tstepA = (size_t)256 * D * 2; S.tstepB = (size_t)256 * D * 2;
;         EpiWin E; E.u = (float*)(pws(p) + OFF_U); E.zb = (bf16_t*)(pws(p) + OFF_ZB); E.rsq = (const float*)(pws(p) + OFF_RSQ) + (size_t)l * MPAD; E.cf = (const float*)(pws(p) + OFF_CS);
;         gemm_phase(lds, S, E, D, D, D, tid); }
;     } else if (sub == 1) { if (PH_MASK & 4)
;         for (int it = bid; it < 1024 + 544 + 580; it += G) {
;             if (it < 1024) sample_ret_unit(p, l, it, lds, tid);
;             else if (it < 1568) kv_unit(p, it - 1024, lds, tid);
;             else pool_item(p, l, it - 1568, tid);
;         }
;     } else if (sub == 2) { if (PH_MASK & 8) {
;         for (int it = bid; it + G < 1024; it += 2 * G) scan_item2(p, l, it, it + G, tid); }
;     } else if (sub == 3) { if (PH_MASK & 16) {
;         SchedPool S; S.init(MPAD, D, G, (bid + 128) % G); S.A = pws(p) + OFF_POOLED; S.Bt = pws(p) + OFF_WPOOL + l * SZ_WPOOL;
;         EpiPool E; E.ain = (bf16_t*)(pws(p) + OFF_AIN); E.zb = (const bf16_t*)(pws(p) + OFF_ZB);
;         gemm_phase(lds, S, E, 512, D, 512, tid);
;         for (int it = bid; it < 544; it += G) ret_out_unit(p, l, it, lds, launder(tid)); }
;     } else if (sub == 4) { if (PH_MASK & 32) {
;         SchedDual S; S.init(MPAD, D, G, bid); S.A = pws(p) + OFF_AIN; S.Bt = pws(p) + OFF_WPR + l * SZ_WPR;
;         EpiDual E; E.merged = (bf16_t*)(pws(p) + OFF_MERGED); E.zb = (const bf16_t*)(pws(p) + OFF_ZB);
;         { const int sidx = bid < 40 ? bid : (bid < 80 ? bid - 40 : 0); E.m1 = (float*)(pws(p) + OFF_M1) + ((size_t)l * 40 + sidx) * 65536; E.flag = (unsigned*)(pws(p) + OFF_BAR + 16384) + (l * 40 + sidx) * 64; }
;         gemm_phase(lds, S, E, D, D, D, tid);
;         if (l == 0 && bid >= 80) for (int it = bid - 80; it < 1440; it += G - 80) conv_item(p, 1, it, lds, launder(tid)); }
;     } else { if (PH_MASK & 64) {
;         SchedPlain S; S.init(MPAD, D, G, bid); S.A = pws(p) + OFF_MERGED; S.Bt = pws(p) + OFF_WOUT + l * SZ_WOUT; S.tstepA = (size_t)256 * D * 2; S.tstepB = (size_t)256 * D * 2;
.LBB0_5:
	s_or_b64 exec, exec, s[0:1]
	s_load_dwordx4 s[84:87], s[88:89], 0x68
	s_load_dwordx2 s[6:7], s[88:89], 0x78
	s_load_dwordx16 s[44:59], s[88:89], 0x0
	s_load_dwordx4 s[8:11], s[88:89], 0x40
	s_mul_i32 s0, s43, s42
	v_mov_b32_e32 v234, 0x3ecc95a3
	v_mov_b32_e32 v190, 0x358637bd
	s_waitcnt lgkmcnt(0)
	s_add_u32 s66, s86, 0x4000000
	s_addc_u32 s67, s87, 0
	s_add_u32 s76, s6, 0xb400000
	s_addc_u32 s77, s7, 0
	s_add_u32 s4, s84, 0x1000
	s_addc_u32 s5, s85, 0
	s_add_u32 s2, s84, 0x1400
	s_addc_u32 s3, s85, 0
	s_add_u32 s72, s84, 0x1800
	s_addc_u32 s73, s85, 0
	s_add_u32 s94, s84, 0x1c00
	s_addc_u32 s95, s85, 0
	s_add_u32 s12, s6, 0x41b28000
	s_addc_u32 s13, s7, 0
	s_add_u32 s68, s6, 0xfe00000
	v_writelane_b32 v253, s12, 5
	s_addc_u32 s69, s7, 0
	v_mov_b32_e32 v235, 0x2000
	v_writelane_b32 v253, s13, 6
	s_add_u32 s12, s6, 0x12300000
	s_addc_u32 s13, s7, 0
	v_writelane_b32 v253, s12, 7
	s_add_u32 s1, s6, 0x8000000
	v_mov_b32_e32 v236, 1
	v_writelane_b32 v253, s13, 8
	v_writelane_b32 v253, s1, 9
	s_addc_u32 s1, s7, 0
	s_cmp_lg_u64 s[8:9], 0
	v_writelane_b32 v253, s1, 10
	s_cselect_b64 s[12:13], -1, 0
	v_writelane_b32 v253, s12, 11
	s_cmp_lg_u64 s[54:55], 0
	v_mov_b64_e32 v[246:247], 0x127
	v_writelane_b32 v253, s13, 12
	s_cselect_b64 s[12:13], -1, 0
	s_add_u32 s96, s6, 0x29628000
	v_writelane_b32 v253, s12, 13
	s_addc_u32 s97, s7, 0
	s_add_u32 s1, s6, 0x8400000
	v_writelane_b32 v253, s13, 14
	v_writelane_b32 v253, s1, 15
	s_addc_u32 s1, s7, 0
	s_add_u32 s12, s6, 0x32a28000
	v_writelane_b32 v253, s1, 16
	s_addc_u32 s13, s7, 0
	v_writelane_b32 v253, s12, 17
	v_mov_b64_e32 v[248:249], 0x128
	v_mov_b32_e32 v237, 0x42800000
	v_writelane_b32 v253, s13, 18
	s_add_u32 s12, s6, 0x16e28000
	s_addc_u32 s13, s7, 0
	v_writelane_b32 v253, s12, 19
	s_add_u32 s1, s6, 0x2e028000
	v_mov_b32_e32 v238, 0x7fc00000
	v_writelane_b32 v253, s13, 20
	v_writelane_b32 v253, s1, 21
	s_addc_u32 s1, s7, 0
	v_writelane_b32 v253, s1, 22
	s_add_u32 s1, s6, 0x41d32000
	v_writelane_b32 v253, s1, 23
	s_addc_u32 s1, s7, 0
	v_writelane_b32 v253, s1, 24
	s_ashr_i32 s1, s42, 31
	v_writelane_b32 v253, s1, 25
	s_add_i32 s1, s42, 0xffffffb0
	v_writelane_b32 v253, s1, 26
	s_add_u32 s1, s56, 0x8000000
	v_writelane_b32 v253, s1, 27
	s_addc_u32 s1, s57, 0
	v_writelane_b32 v253, s1, 28
	s_add_u32 s1, s6, 0x4000000
	v_writelane_b32 v253, s1, 29
	s_addc_u32 s1, s7, 0
	v_writelane_b32 v253, s1, 30
	s_load_dword s1, s[88:89], 0x90
	v_mov_b32_e32 v239, 0xff800000
	v_not_b32_e32 v240, 63
	v_mov_b32_e32 v196, 0x3f317218
	v_mov_b32_e32 v241, 0x1e000
	s_waitcnt lgkmcnt(0)
; #define LAS __attribute__((address_space(3)))
; __global__ void __launch_bounds__(512, 2) mega_kernel(Params p, unsigned* bar) {
;     cg::grid_group grid = cg::this_grid();
;     LAS unsigned char* lds = (LAS unsigned char*)smem_dyn;
;     ...
;     volatile LAS unsigned* st = (volatile LAS unsigned*)(lds + LDS_ST_OFF);
;     if (threadIdx.x == 0) { st[0] = 0u; st[1] = 0u; }
;     __syncthreads();
;     (void)xcd_barrier_post(bar, st);
;     int ph = 0, rep = 0;
; #pragma unroll 1
;     while (ph < 14) {
;         int tid = threadIdx.x; asm volatile("" : "+v"(tid));
;         int bid = blockIdx.x; asm volatile("" : "+s"(bid)); bid = __builtin_amdgcn_readfirstlane(bid);
;         run_phase(p, ph, lds, tid, bid);
	s_mul_i32 s0, s0, s1
	v_writelane_b32 v253, s0, 31
	s_add_u32 s0, s54, 0x2000
	s_addc_u32 s1, s55, 0
	v_writelane_b32 v253, s0, 32
	v_mov_b32_e32 v242, 0x37000000
	v_mov_b32_e32 v243, 0x7f800000
	v_writelane_b32 v253, s1, 33
	s_add_u32 s0, s6, 0x27128000
	s_addc_u32 s1, s7, 0
	v_writelane_b32 v253, s0, 34
	s_mov_b32 s78, 0x800000
	s_movk_i32 s74, 0x7000
	v_writelane_b32 v253, s1, 35
	s_add_u32 s0, s6, 0x3d728000
	s_addc_u32 s1, s7, 0
	s_lshl_b32 s60, s42, 1
	s_add_u32 s41, s6, 0x34f28000
	s_addc_u32 s40, s7, 0
	v_writelane_b32 v253, s1, 36
	s_add_u32 s1, s86, 0x48f0000
	v_writelane_b32 v253, s1, 37
	s_addc_u32 s1, s87, 0
	s_add_u32 s12, s6, 0x12428000
	v_writelane_b32 v253, s1, 38
	s_addc_u32 s13, s7, 0
	v_writelane_b32 v253, s12, 39
	s_mov_b32 s75, 0xc2fc0000
	s_mov_b32 s81, 0
	v_writelane_b32 v255, s81, 4
	v_writelane_b32 v255, s81, 5
	v_writelane_b32 v255, s81, 6
	v_writelane_b32 v255, s81, 7
	v_writelane_b32 v253, s13, 40
	s_add_u32 s12, s86, 0x4800000
	s_addc_u32 s13, s87, 0
	v_writelane_b32 v253, s12, 41
	s_mov_b32 s91, 0
	s_mov_b64 s[92:93], 0x80
	v_writelane_b32 v253, s13, 42
	s_add_u32 s12, s86, 0x58f0000
	s_addc_u32 s13, s87, 0
	v_writelane_b32 v253, s12, 43
	s_add_u32 s1, s86, 0x76f0000
	s_nop 0
	v_writelane_b32 v253, s13, 44
	v_writelane_b32 v253, s1, 45
	s_addc_u32 s1, s87, 0
	v_writelane_b32 v253, s1, 46
	s_add_u32 s1, s6, 0xa400000
	v_writelane_b32 v253, s1, 47
	s_addc_u32 s1, s7, 0
	s_add_u32 s12, s6, 0x12309400
	v_writelane_b32 v253, s1, 48
	s_addc_u32 s13, s7, 0
	v_writelane_b32 v253, s12, 49
	s_sub_i32 s1, s42, 40
	s_nop 0
	v_writelane_b32 v253, s13, 50
	v_writelane_b32 v253, s1, 51
	s_add_u32 s1, s58, 0x400000
	v_writelane_b32 v253, s1, 52
	s_addc_u32 s1, s59, 0
	v_writelane_b32 v253, s1, 53
	s_add_u32 s1, s6, 0x8200000
	v_writelane_b32 v253, s1, 54
	s_addc_u32 s1, s7, 0
	v_writelane_b32 v253, s1, 55
	s_add_u32 s1, s8, 0x2000
	v_writelane_b32 v253, s1, 56
	v_writelane_b32 v253, s8, 57
	s_addc_u32 s1, s9, 0
	s_nop 0
	v_writelane_b32 v253, s9, 58
	v_writelane_b32 v253, s10, 59
	v_writelane_b32 v253, s11, 60
	s_add_u32 s8, s70, 0x200
	v_writelane_b32 v253, s1, 61
	s_addc_u32 s9, s71, 0
	v_writelane_b32 v253, s8, 62
	s_nop 1
	v_writelane_b32 v253, s9, 63
	s_add_u32 s8, s70, 0x1000
	s_addc_u32 s9, s71, 0
	v_writelane_b32 v254, s8, 0
	s_nop 1
	v_writelane_b32 v254, s9, 1
	s_add_u32 s8, s70, 0x1100
	s_addc_u32 s9, s71, 0
	v_writelane_b32 v254, s8, 2
	s_nop 1
	v_writelane_b32 v254, s9, 3
	s_add_u32 s8, s70, 0x1200
	s_addc_u32 s9, s71, 0
	v_writelane_b32 v254, s8, 4
	s_nop 1
	v_writelane_b32 v254, s9, 5
	s_add_u32 s8, s70, 0x1300
	s_addc_u32 s9, s71, 0
	v_writelane_b32 v254, s8, 6
	s_nop 1
	v_writelane_b32 v254, s9, 7
	s_add_u32 s8, s70, 0x3400
	s_addc_u32 s9, s71, 0
	v_writelane_b32 v254, s8, 8
	s_nop 1
	v_writelane_b32 v254, s9, 9
	s_add_u32 s8, s70, 0x3500
	s_addc_u32 s9, s71, 0
	v_writelane_b32 v254, s8, 10
	s_cmp_eq_u32 s43, 7
	s_mov_b32 s43, s0
	v_writelane_b32 v254, s9, 11
	s_cselect_b64 s[0:1], -1, 0
	v_writelane_b32 v254, s0, 12
	s_lshl_b32 s8, s42, 5
	s_nop 0
	v_writelane_b32 v254, s1, 13
	s_abs_i32 s0, s42
	v_cvt_f32_u32_e32 v1, s0
	v_writelane_b32 v254, s0, 14
	s_sub_i32 s0, 0, s0
	v_rcp_iflag_f32_e32 v1, v1
	s_nop 0
	v_mul_f32_e32 v1, 0x4f7ffffe, v1
	v_cvt_u32_f32_e32 v1, v1
	s_nop 0
	v_readfirstlane_b32 s1, v1
	s_mul_i32 s0, s0, s1
	s_mul_hi_u32 s0, s1, s0
	s_add_i32 s0, s1, s0
	v_lshrrev_b32_e32 v1, 20, v0
	v_lshrrev_b32_e32 v0, 10, v0
	v_writelane_b32 v254, s0, 15
	v_or_b32_e32 v0, v0, v1
	s_movk_i32 s0, 0x3ff
	v_and_or_b32 v0, v0, s0, v191
	s_lshl_b32 s0, s42, 4
	s_lshl_b32 s1, s42, 8
	v_writelane_b32 v254, s0, 16
	s_add_i32 s9, s1, 0xffffb000
	v_writelane_b32 v254, s9, 17
	s_lshl_b32 s9, s42, 9
	v_writelane_b32 v254, s9, 18
	s_lshl_b32 s9, s42, 10
	s_lshl_b32 s0, s42, 3
	v_writelane_b32 v254, s9, 19
	s_add_u32 s10, s6, 0x12426000
	v_writelane_b32 v254, s6, 20
	s_addc_u32 s11, s7, 0
	v_mov_b32_e32 v1, 0
	v_writelane_b32 v254, s7, 21
	v_writelane_b32 v254, s10, 22
	s_mov_b32 s6, s42
	s_nop 0
	v_writelane_b32 v254, s11, 23
	v_writelane_b32 v254, s6, 24
	v_writelane_b32 v254, s0, 25
	s_addk_i32 s0, 0xfec0
	v_writelane_b32 v254, s0, 26
	v_writelane_b32 v254, s1, 27
	s_add_i32 s0, s1, 0xffffd800
	v_writelane_b32 v254, s0, 28
	v_writelane_b32 v254, s8, 29
	s_add_i32 s0, s8, 0xfffffb00
	v_writelane_b32 v254, s0, 30
	s_add_i32 s0, 0, 0x10400
	v_writelane_b32 v254, s0, 31
	s_add_i32 s0, 0, 0x23ff0
	v_writelane_b32 v254, s0, 32
	s_add_i32 s0, 0, 0x23ff4
	v_writelane_b32 v254, s0, 33
	v_cmp_eq_u32_e64 s[0:1], 0, v0
	s_nop 1
	v_writelane_b32 v254, s0, 34
	s_nop 1
	v_writelane_b32 v254, s1, 35
	v_writelane_b32 v254, s43, 36
	v_writelane_b32 v254, s60, 37
	v_writelane_b32 v254, s41, 38
	v_writelane_b32 v254, s40, 39
	v_writelane_b32 v254, s88, 40
	s_nop 1
	v_writelane_b32 v254, s89, 41
	v_writelane_b32 v254, s84, 42
	s_nop 1
	v_writelane_b32 v254, s85, 43
	v_writelane_b32 v254, s86, 44
	v_writelane_b32 v254, s87, 45
	s_branch .LBB0_9

; __device__ __forceinline__ void run_phase(const Params& p, int ph, LAS unsigned char* lds, const int tid, const int bid) {
;     ...
;     } else if (sub == 1) { if (PH_MASK & 4)
;         for (int it = bid; it < 1024 + 544 + 580; it += G) {
;             if (it < 1024) sample_ret_unit(p, l, it, lds, tid);
;             else if (it < 1568) kv_unit(p, it - 1024, lds, tid);
;             else pool_item(p, l, it - 1568, tid);
;         }
.Lz1_p2start:
	s_cmpk_lg_u32 s42, 0x100
	s_cbranch_scc1 .Lz1_p2go
	s_cmpk_gt_u32 s82, 63
	s_cbranch_scc1 .Lz1_p2go
	v_readlane_b32 s18, v255, 7
	s_mov_b32 s19, 0
	s_cmp_eq_u32 s18, 0
	s_cbranch_scc1 .Lz1_divert
	v_writelane_b32 v255, s19, 7
	s_branch .Lz1_p2go
.Lz1_divert:
	s_mov_b32 s19, 1
	s_nop 0
	v_writelane_b32 v255, s19, 6
	v_writelane_b32 v255, s7, 8
	s_branch .Lz1_p1entry
.Lz1_p2go:
	s_cmpk_gt_i32 s82, 0x863
	s_cbranch_scc1 .LBB0_546
	v_readlane_b32 s0, v254, 46
	v_readlane_b32 s1, v254, 47
	s_mov_b32 s1, s91
	v_readlane_b32 s8, v253, 57
	s_lshl_b64 s[22:23], s[0:1], 7
	s_lshl_b64 s[24:25], s[0:1], 2
	s_lshl_b64 s[26:27], s[0:1], 10
	s_mov_b32 s6, s0
	s_lshl_b64 s[0:1], s[0:1], 13
	v_readlane_b32 s10, v253, 59
	v_readlane_b32 s11, v253, 60
	s_add_u32 s34, s10, s0
	v_writelane_b32 v254, s6, 46
	s_addc_u32 s35, s11, s1
	s_mov_b32 s38, s82
	s_cmpk_lg_u32 s42, 0x100
	s_cbranch_scc1 .Lp2_fwd0
	s_bitcmp1_b32 s82, 3
	s_cbranch_scc0 .Lp2_fwd0
	s_sub_i32 s0, 0x863, s82
	s_andn2_b32 s0, s0, 0xff
	s_add_i32 s38, s82, s0

; #define G_STAGE(bufoff, gbase, voff) do { _Pragma("unroll") for (int _i = 0; _i < 2; ++_i) \
;         __builtin_amdgcn_global_load_lds((const unsigned*)((const char*)(gbase) + (voff)[_i]), (LAS unsigned*)(lds + (bufoff) + ldsw + _i * 8192), 16, 0, 0); } while (0)
; #define G_WAIT_V(n) asm volatile("s_waitcnt vmcnt(" #n ")" ::: "memory")
; #define G_BAR __builtin_amdgcn_s_barrier()
;     __device__ bool next(int i, Unit& u) const {
;         const long L = (long)i * G + c; if (L >= nwg) return false;
;         int wgid = (int)L; { const int q = nwg / NXCD, r = nwg % NXCD, xcd = wgid % NXCD, off = wgid / NXCD; wgid = (xcd < r ? xcd * (q + 1) : r * (q + 1) + (xcd - r) * q) + off; }
;         const int nig = WGM * nN, gid = wgid / nig, fm = gid * WGM, gsz = (nM - fm) < WGM ? (nM - fm) : WGM;
;         u.pm = fm + ((wgid % nig) % gsz); u.pn = (wgid % nig) / gsz; u.mode = 0; return true;
; template <class Epi, class Sched>
; __device__ __forceinline__ void gemm_phase(LAS unsigned char* lds, const Sched& S, const Epi& E, const int K, const int lda, const int ldb, const int tid) {
;     ...
;     const char* cA; const char* cB; S.ptrs(cur, cA, cB);
;     G_STAGE(G_SB(0, 0), cB, voffB); G_STAGE(G_SA(0, 0), cA, voffA); G_STAGE(G_SB(0, 1), cB + hstepB, voffB); G_STAGE(G_SA(0, 1), cA + hstepA, voffA);
;     if (wr == 1) G_BAR;
;     G_WAIT_V(4); G_BAR;
;     G_STAGE(G_SB(1, 0), cB + kstep, voffB); G_STAGE(G_SA(1, 0), cA + kstep, voffA); G_STAGE(G_SB(1, 1), cB + hstepB + kstep, voffB);
;     G_WAIT_V(6); G_BAR;
.Lz1_p1entry:
	s_cmpk_gt_i32 s82, 0x93f
	v_readfirstlane_b32 s24, v244
	s_cbranch_scc1 .LBB0_582
	v_lshlrev_b32_e32 v0, 4, v244
	s_waitcnt vmcnt(0)
	v_add_u32_e32 v2, 0x2000, v0
	v_ashrrev_i32_e32 v3, 31, v2
	v_lshrrev_b32_e32 v3, 22, v3
	v_add_u32_e32 v3, v2, v3
	v_ashrrev_i32_e32 v10, 10, v3
	v_mul_i32_i24_e32 v3, 0x400, v10
	v_sub_u32_e32 v2, v2, v3
	v_lshrrev_b32_e32 v3, 4, v2
	v_bitop3_b32 v2, v3, v2, 32 bitop3:0x6c
	v_ashrrev_i32_e32 v3, 31, v2
	v_readlane_b32 s14, v254, 46
	v_lshrrev_b32_e32 v3, 26, v3
	v_readlane_b32 s15, v254, 47
	v_add_u32_e32 v3, v2, v3
	v_lshlrev_b32_e32 v4, 3, v10
	s_mov_b32 s15, s91
	v_ashrrev_i32_e32 v11, 6, v3
	v_and_b32_e32 v4, -16, v4
	s_lshl_b64 s[0:1], s[14:15], 26
	v_readlane_b32 s6, v254, 20
	v_add_u32_e32 v4, v11, v4
	s_add_u32 s25, s6, s0
	v_and_b32_e32 v5, 3, v11
	s_mov_b32 s0, 0xfffe0
	v_lshrrev_b32_e32 v6, 2, v4
	v_lshlrev_b32_e32 v7, 1, v4
	v_and_b32_e32 v3, 0xc0, v3
	v_and_or_b32 v5, v4, s0, v5
	v_and_b32_e32 v6, 4, v6
	v_and_b32_e32 v7, 24, v7
	v_sub_u32_e32 v2, v2, v3
	v_or3_b32 v5, v5, v6, v7
	v_lshlrev_b32_e32 v6, 5, v10
	v_ashrrev_i16_sdwa v2, v236, sext(v2) dst_sel:DWORD dst_unused:UNUSED_PAD src0_sel:DWORD src1_sel:BYTE_0
	v_and_b32_e32 v6, 32, v6
	v_bfe_i32 v12, v2, 0, 16
	v_add_lshl_u32 v2, v6, v12, 1
	v_lshl_add_u32 v146, v5, 12, v2
	v_lshl_add_u32 v148, v4, 12, v2
	v_bfe_i32 v2, v244, 27, 1
	v_lshrrev_b32_e32 v2, 22, v2
	v_add_u32_e32 v2, v0, v2
	v_and_b32_e32 v2, 0xfffffc00, v2
	v_sub_u32_e32 v0, v0, v2
	v_lshrrev_b32_e32 v2, 4, v0
	v_ashrrev_i32_e32 v3, 31, v244
	v_bitop3_b32 v0, v2, v0, 32 bitop3:0x6c
	v_lshrrev_b32_e32 v3, 26, v3
	v_ashrrev_i32_e32 v2, 31, v0
	v_add_u32_e32 v3, v244, v3
	v_lshrrev_b32_e32 v2, 26, v2
	v_ashrrev_i32_e32 v14, 6, v3
	v_add_u32_e32 v2, v0, v2
	v_lshlrev_b32_e32 v3, 3, v14
	v_readlane_b32 s7, v254, 21
	v_ashrrev_i32_e32 v13, 6, v2
	v_and_b32_e32 v3, -16, v3
	s_addc_u32 s26, s7, s1
	v_add_u32_e32 v3, v13, v3
	v_and_b32_e32 v4, 3, v13
	s_ashr_i32 s28, s82, 31
	v_and_or_b32 v4, v3, s0, v4
	s_lshr_b32 s0, s28, 29
	s_add_i32 s0, s82, s0
	s_ashr_i32 s10, s24, 6
	s_ashr_i32 s1, s0, 3
	s_and_b32 s0, s0, -8
	s_ashr_i32 s7, s24, 8
	s_lshl_b32 s27, s10, 10
	s_sub_i32 s0, s82, s0
	s_cmp_lt_i32 s0, 0
	s_movk_i32 s6, 0x129
	s_cselect_b32 s6, s6, 0x128
	s_cmpk_eq_u32 s42, 0x100
	s_cselect_b32 s6, 0x120, s6
	s_mul_i32 s0, s6, s0
	s_add_i32 s0, s0, s1
	v_readlane_b32 s1, v255, 6
	s_cmp_eq_u32 s1, 0
	s_cbranch_scc1 .Lz1_nf
	s_add_i32 s0, s82, 0x900
.Lz1_nf:
	s_ashr_i32 s1, s0, 31
	s_lshr_b32 s1, s1, 23
	v_lshrrev_b32_e32 v5, 2, v3
	v_lshlrev_b32_e32 v6, 1, v3
	v_and_b32_e32 v2, 0xc0, v2
	s_add_i32 s1, s0, s1
	v_and_b32_e32 v5, 4, v5
	v_and_b32_e32 v6, 24, v6
	v_sub_u32_e32 v0, v0, v2
	s_ashr_i32 s6, s1, 9
	v_or3_b32 v4, v4, v5, v6
	v_lshlrev_b32_e32 v5, 5, v14
	v_ashrrev_i16_sdwa v0, v236, sext(v0) dst_sel:DWORD dst_unused:UNUSED_PAD src0_sel:DWORD src1_sel:BYTE_0
	s_lshl_b32 s8, s6, 3
	v_and_b32_e32 v5, 32, v5
	v_bfe_i32 v15, v0, 0, 16
	s_sub_i32 s6, 37, s8
	v_add_lshl_u32 v0, v5, v15, 1
	s_min_u32 s9, s6, 8
	s_and_b32 s1, s1, 0xfffffe00
	v_lshl_add_u32 v150, v4, 12, v0
	s_sub_i32 s11, s0, s1
	v_cvt_f32_ubyte0_e32 v4, s9
	v_cvt_f32_i32_e32 v2, s11
	v_rcp_iflag_f32_e32 v5, v4
	v_lshl_add_u32 v152, v3, 12, v0
	s_ashr_i32 s0, s11, 30
	s_or_b32 s6, s0, 1
	v_mul_f32_e32 v0, v2, v5
	v_trunc_f32_e32 v0, v0
	v_fma_f32 v2, -v0, v4, v2
	v_cvt_i32_f32_e32 v0, v0
	v_cmp_ge_f32_e64 s[0:1], |v2|, v4
	s_and_b64 s[0:1], s[0:1], exec
	s_cselect_b32 s0, s6, 0
	v_readfirstlane_b32 s1, v0
	s_add_i32 s6, s1, s0
	s_mul_i32 s0, s6, s9
	s_sub_i32 s0, s11, s0
	s_sext_i32_i16 s0, s0
	s_add_i32 s0, s8, s0
	s_ashr_i32 s1, s0, 31
	s_bfe_i64 s[12:13], s[6:7], 0x100000
	s_lshl_b64 s[8:9], s[0:1], 20
	s_lshl_b64 s[12:13], s[12:13], 20
	s_add_u32 s20, s25, s12
	s_addc_u32 s21, s26, s13
	s_add_i32 s29, s27, 0
	s_add_i32 m0, s29, 0x10000
	v_mov_b32_e32 v151, v1
	global_load_lds_dwordx4 v150, s[20:21]
	s_add_i32 m0, s29, 0x12000
	s_add_u32 s18, s68, s8
	global_load_lds_dwordx4 v146, s[20:21]
	s_addc_u32 s19, s69, s9
	s_mov_b32 m0, s29
	s_add_i32 s30, s29, 0x2000
	global_load_lds_dwordx4 v152, s[18:19]
	s_mov_b32 m0, s30
	s_add_u32 s8, s20, 0x80000
	global_load_lds_dwordx4 v148, s[18:19]
	s_addc_u32 s9, s21, 0
	s_add_i32 m0, s29, 0x14000
	v_mov_b32_e32 v147, v1
	global_load_lds_dwordx4 v150, s[8:9]
	s_add_i32 m0, s29, 0x16000
	v_mov_b32_e32 v153, v1
	global_load_lds_dwordx4 v146, s[8:9]
	s_add_u32 s8, s18, 0x80000
	s_addc_u32 s9, s19, 0
	s_add_i32 s31, s29, 0x4000
	s_mov_b32 m0, s31
	s_add_i32 s34, s29, 0x6000
	global_load_lds_dwordx4 v152, s[8:9]
	s_mov_b32 m0, s34
	v_mov_b32_e32 v149, v1
	global_load_lds_dwordx4 v148, s[8:9]
	v_lshl_add_u64 v[8:9], s[20:21], 0, v[150:151]
	v_lshl_add_u64 v[6:7], s[20:21], 0, v[146:147]
	v_lshl_add_u64 v[4:5], s[18:19], 0, v[152:153]
	s_cmp_lg_u32 s7, 1
	v_lshl_add_u64 v[2:3], s[18:19], 0, v[148:149]
	s_cbranch_scc1 .LBB0_551
	s_barrier

;     __device__ bool next(int i, Unit& u) const {
;         const long L = (long)i * G + c; if (L >= nwg) return false;
;         int wgid = (int)L; { const int q = nwg / NXCD, r = nwg % NXCD, xcd = wgid % NXCD, off = wgid / NXCD; wgid = (xcd < r ? xcd * (q + 1) : r * (q + 1) + (xcd - r) * q) + off; }
;         const int nig = WGM * nN, gid = wgid / nig, fm = gid * WGM, gsz = (nM - fm) < WGM ? (nM - fm) : WGM;
;         u.pm = fm + ((wgid % nig) % gsz); u.pn = (wgid % nig) / gsz; u.mode = 0; return true;
; template <class Epi, class Sched>
; __device__ __forceinline__ void gemm_phase(LAS unsigned char* lds, const Sched& S, const Epi& E, const int K, const int lda, const int ldb, const int tid) {
;     ...
;         const bool has_next = S.next(ui + 1, nxt);
;         const char* nA = cA; const char* nB = cB; if (has_next) S.ptrs(nxt, nA, nB);
.LBB0_553:
	s_add_i32 s37, s37, 1
	v_readlane_b32 s1, v253, 25
	v_readlane_b32 s7, v254, 24
	s_mul_i32 s1, s37, s1
	s_mul_hi_u32 s6, s37, s7
	s_add_i32 s6, s6, s1
	s_mul_i32 s1, s37, s7
	s_add_u32 s14, s1, s82
	s_addc_u32 s15, s6, s28
	v_readlane_b32 s6, v255, 6
	s_nop 0
	s_lshl_b32 s6, s6, 12
	s_add_u32 s14, s14, s6
	s_addc_u32 s15, s15, 0
	v_mov_b64_e32 v[2:3], 0x93f
	s_cmpk_lg_u32 s42, 0x100
	s_cbranch_scc1 .Lz1_b0
	v_mov_b32_e32 v2, 0x8ff
.Lz1_b0:
	v_cmp_gt_i64_e64 s[6:7], s[14:15], v[2:3]
	s_and_b64 vcc, exec, s[6:7]
	s_cbranch_vccnz .LBB0_555
	s_ashr_i32 s1, s14, 31
	s_lshr_b32 s1, s1, 29
	s_add_i32 s1, s14, s1
	s_ashr_i32 s10, s1, 3
	s_and_b32 s1, s1, -8
	s_sub_i32 s1, s14, s1
	s_cmp_lt_i32 s1, 0
	s_movk_i32 s11, 0x129
	s_cselect_b32 s11, s11, 0x128
	s_cmpk_eq_u32 s42, 0x100
	s_cselect_b32 s11, 0x120, s11
	s_mul_i32 s1, s11, s1
	s_add_i32 s1, s1, s10
	s_cmpk_lg_u32 s42, 0x100
	s_cbranch_scc1 .Lz1_nm
	s_cmpk_lt_i32 s14, 0x900
	s_cbranch_scc1 .Lz1_nm
	s_mov_b32 s1, s14
.Lz1_nm:
	s_ashr_i32 s10, s1, 31
	s_lshr_b32 s10, s10, 23
	s_add_i32 s10, s1, s10
	s_ashr_i32 s11, s10, 9
	s_lshl_b32 s11, s11, 3
	s_sub_i32 s12, 37, s11
	s_min_i32 s12, s12, 8
	s_abs_i32 s13, s12
	v_cvt_f32_u32_e32 v0, s13
	s_sub_i32 s17, 0, s13
	s_and_b32 s10, s10, 0xfffffe00
	s_sub_i32 s1, s1, s10
	v_rcp_iflag_f32_e32 v0, v0
	s_abs_i32 s10, s1
	s_xor_b32 s16, s1, s12
	s_ashr_i32 s16, s16, 31
	v_mul_f32_e32 v0, 0x4f7ffffe, v0
	v_cvt_u32_f32_e32 v0, v0
	s_nop 0
	v_readfirstlane_b32 s22, v0
	s_mul_i32 s17, s17, s22
	s_mul_hi_u32 s17, s22, s17
	s_add_i32 s22, s22, s17
	s_mul_hi_u32 s17, s10, s22
	s_mul_i32 s22, s17, s13
	s_sub_i32 s10, s10, s22
	s_add_i32 s23, s17, 1
	s_sub_i32 s22, s10, s13
	s_cmp_ge_u32 s10, s13
	s_cselect_b32 s17, s23, s17
	s_cselect_b32 s10, s22, s10
	s_add_i32 s22, s17, 1
	s_cmp_ge_u32 s10, s13
	s_cselect_b32 s10, s22, s17
	s_xor_b32 s10, s10, s16
	s_sub_i32 s10, s10, s16
	s_mul_i32 s12, s10, s12
	s_sub_i32 s1, s1, s12
	s_add_i32 s12, s1, s11
.LBB0_555:
	v_mov_b64_e32 v[2:3], 0x940
	s_cmpk_lg_u32 s42, 0x100
	s_cbranch_scc1 .Lz1_b1
	v_mov_b32_e32 v2, 0x900
.Lz1_b1:
	s_ashr_i32 s13, s12, 31
	v_cmp_lt_i64_e32 vcc, s[14:15], v[2:3]
	s_lshl_b64 s[14:15], s[12:13], 20
	s_add_u32 s14, s68, s14
	s_addc_u32 s15, s69, s15
	s_ashr_i32 s11, s10, 31
	s_lshl_b64 s[16:17], s[10:11], 20
	s_add_u32 s16, s25, s16
	s_addc_u32 s17, s26, s17
	s_and_b64 s[22:23], vcc, exec
	s_cselect_b32 s1, s15, s19
	s_cselect_b32 s11, s14, s18
	s_cselect_b32 s13, s17, s21
	s_cselect_b32 s33, s16, s20
	s_add_u32 s18, s18, 0x80080
	s_addc_u32 s19, s19, 0
	s_add_u32 s39, s20, 0x100
	v_mov_b32_e32 v2, 0
	s_addc_u32 s40, s21, 0
	s_mov_b32 s41, -2
	v_mov_b32_e32 v3, v2
	v_mov_b32_e32 v4, v2
	v_mov_b32_e32 v5, v2
	v_mov_b32_e32 v6, v2
	v_mov_b32_e32 v7, v2
	v_mov_b32_e32 v8, v2
	v_mov_b32_e32 v9, v2
	v_mov_b32_e32 v18, v2
	v_mov_b32_e32 v19, v2
	v_mov_b32_e32 v20, v2
	v_mov_b32_e32 v21, v2
	v_mov_b32_e32 v22, v2
	v_mov_b32_e32 v23, v2
	v_mov_b32_e32 v24, v2
	v_mov_b32_e32 v25, v2
	v_mov_b32_e32 v34, v2
	v_mov_b32_e32 v35, v2
	v_mov_b32_e32 v36, v2
	v_mov_b32_e32 v37, v2
	v_mov_b32_e32 v38, v2
	v_mov_b32_e32 v39, v2
	v_mov_b32_e32 v40, v2
	v_mov_b32_e32 v41, v2
	v_mov_b32_e32 v50, v2
	v_mov_b32_e32 v51, v2
	v_mov_b32_e32 v52, v2
	v_mov_b32_e32 v53, v2
	v_mov_b32_e32 v54, v2
	v_mov_b32_e32 v55, v2
	v_mov_b32_e32 v56, v2
	v_mov_b32_e32 v57, v2
	v_mov_b32_e32 v10, v2
	v_mov_b32_e32 v11, v2
	v_mov_b32_e32 v12, v2
	v_mov_b32_e32 v13, v2
	v_mov_b32_e32 v14, v2
	v_mov_b32_e32 v15, v2
	v_mov_b32_e32 v16, v2
	v_mov_b32_e32 v17, v2
	v_mov_b32_e32 v26, v2
	v_mov_b32_e32 v27, v2
	v_mov_b32_e32 v28, v2
	v_mov_b32_e32 v29, v2
	v_mov_b32_e32 v30, v2
	v_mov_b32_e32 v31, v2
	v_mov_b32_e32 v32, v2
	v_mov_b32_e32 v33, v2
	v_mov_b32_e32 v42, v2
	v_mov_b32_e32 v43, v2
	v_mov_b32_e32 v44, v2
	v_mov_b32_e32 v45, v2
	v_mov_b32_e32 v46, v2
	v_mov_b32_e32 v47, v2
	v_mov_b32_e32 v48, v2
	v_mov_b32_e32 v49, v2
	v_mov_b32_e32 v58, v2
	v_mov_b32_e32 v59, v2
	v_mov_b32_e32 v60, v2
	v_mov_b32_e32 v61, v2
	v_mov_b32_e32 v62, v2
	v_mov_b32_e32 v63, v2
	v_mov_b32_e32 v64, v2
	v_mov_b32_e32 v65, v2
	v_mov_b32_e32 v66, v2
	v_mov_b32_e32 v67, v2
	v_mov_b32_e32 v68, v2
	v_mov_b32_e32 v69, v2
	v_mov_b32_e32 v70, v2
	v_mov_b32_e32 v71, v2
	v_mov_b32_e32 v72, v2
	v_mov_b32_e32 v73, v2
	v_mov_b32_e32 v82, v2
	v_mov_b32_e32 v83, v2
	v_mov_b32_e32 v84, v2
	v_mov_b32_e32 v85, v2
	v_mov_b32_e32 v86, v2
	v_mov_b32_e32 v87, v2
	v_mov_b32_e32 v88, v2
	v_mov_b32_e32 v89, v2
	v_mov_b32_e32 v98, v2
	v_mov_b32_e32 v99, v2
	v_mov_b32_e32 v100, v2
	v_mov_b32_e32 v101, v2
	v_mov_b32_e32 v102, v2
	v_mov_b32_e32 v103, v2
	v_mov_b32_e32 v104, v2
	v_mov_b32_e32 v105, v2
	v_mov_b32_e32 v114, v2
	v_mov_b32_e32 v115, v2
	v_mov_b32_e32 v116, v2
	v_mov_b32_e32 v117, v2
	v_mov_b32_e32 v118, v2
	v_mov_b32_e32 v119, v2
	v_mov_b32_e32 v120, v2
	v_mov_b32_e32 v121, v2
	v_mov_b32_e32 v74, v2
	v_mov_b32_e32 v75, v2
	v_mov_b32_e32 v76, v2
	v_mov_b32_e32 v77, v2
	v_mov_b32_e32 v78, v2
	v_mov_b32_e32 v79, v2
	v_mov_b32_e32 v80, v2
	v_mov_b32_e32 v81, v2
	v_mov_b32_e32 v90, v2
	v_mov_b32_e32 v91, v2
	v_mov_b32_e32 v92, v2
	v_mov_b32_e32 v93, v2
	v_mov_b32_e32 v94, v2
	v_mov_b32_e32 v95, v2
	v_mov_b32_e32 v96, v2
	v_mov_b32_e32 v97, v2
	v_mov_b32_e32 v106, v2
	v_mov_b32_e32 v107, v2
	v_mov_b32_e32 v108, v2
	v_mov_b32_e32 v109, v2
	v_mov_b32_e32 v110, v2
	v_mov_b32_e32 v111, v2
	v_mov_b32_e32 v112, v2
	v_mov_b32_e32 v113, v2
	v_mov_b32_e32 v122, v2
	v_mov_b32_e32 v123, v2
	v_mov_b32_e32 v124, v2
	v_mov_b32_e32 v125, v2
	v_mov_b32_e32 v126, v2
	v_mov_b32_e32 v127, v2
	v_mov_b32_e32 v128, v2
	v_mov_b32_e32 v129, v2

; #define G_WAIT_V(n) asm volatile("s_waitcnt vmcnt(" #n ")" ::: "memory")
; #define G_BAR __builtin_amdgcn_s_barrier()
; template <class Epi, class Sched>
; __device__ __forceinline__ void gemm_phase(LAS unsigned char* lds, const Sched& S, const Epi& E, const int K, const int lda, const int ldb, const int tid) {
;     ...
;         const bool keep = E(acc, cur, wr, wc, fr, fq);
;         if (!has_next) break;
;         if (!keep)
; #pragma unroll
;         for (int a = 0; a < 2; ++a)
; #pragma unroll
;             for (int b = 0; b < 2; ++b)
; #pragma unroll
;                 for (int m = 0; m < 4; ++m)
; #pragma unroll
;                     for (int n = 0; n < 2; ++n) acc[a][b][m][n] = (f32x4){0.f, 0.f, 0.f, 0.f};
;         cur = nxt; cA = nA; cB = nB; ++ui;
;     }
;     G_WAIT_V(0);
;     if (wr == 0) G_BAR;
;     G_BAR;
.LBB0_581:
	s_barrier
	v_readlane_b32 s18, v255, 6
	s_mov_b32 s19, 0
	s_cmp_eq_u32 s18, 0
	s_cbranch_scc1 .Lz1_noforce
	v_writelane_b32 v255, s19, 6
	s_mov_b32 s19, 1
	s_nop 0
	v_writelane_b32 v255, s19, 7
	v_readlane_b32 s7, v255, 8
	s_branch .Lz1_p2start
.Lz1_noforce:
.LBB0_582:
	s_branch .LBB0_660
